# P2 epilogue stores sc0 sc1
# baseline (speedup 1.0000x reference)
; __device__ __forceinline__ unsigned cvt_pk_bf16(float lo, float hi) { unsigned r; asm volatile("v_cvt_pk_bf16_f32 %0, %1, %2" : "=v"(r) : "v"(lo), "v"(hi)); return r; }
;     __device__ __forceinline__ void operator()(const f32x4 (&acc)[2][2][4][2], const Unit& u, int wr, int wc, int fr, int fq) const {
;     ...
;             bf16_t* base; int ld, ct; float sc = 1.f;
;             if (pn < 4) { base = Q; ld = 1024; ct = pn; sc = qscale; } else if (pn < 8) { base = Kb; ld = 1024; ct = pn - 4; } else if (pn < 12) { base = V; ld = 1024; ct = pn - 8; }
;             else if (pn < 14) { base = U; ld = 512; ct = pn - 12; } else { base = G; ld = 2048; ct = pn - 14; }
;             const int row0 = u.pm * BM + wr * 64 + fr, col0 = ct * 256 + wc * 32 + 8 * fq;
; #pragma unroll
;             for (int ai = 0; ai < 2; ++ai)
; #pragma unroll
;                 for (int m = 0; m < 4; ++m) { bf16_t* rowp = base + (size_t)(row0 + ai * HALF + m * 16) * ld + col0;
; #pragma unroll
;                     for (int bj = 0; bj < 2; ++bj) { const f32x4 v0 = acc[ai][bj][m][0] * sc, v1 = acc[ai][bj][m][1] * sc;
;                         u32x4 w; w.x = cvt_pk_bf16(v0[0], v0[1]); w.y = cvt_pk_bf16(v0[2], v0[3]); w.z = cvt_pk_bf16(v1[0], v1[1]); w.w = cvt_pk_bf16(v1[2], v1[3]);
;                         __builtin_nontemporal_store(w, (u32x4*)(rowp + bj * HALF)); } }
.LBB0_215:
	s_cmp_lt_u32 s73, 14
	s_cselect_b64 s[60:61], -1, 0
	s_and_b64 s[66:67], s[60:61], exec
	s_cselect_b32 s13, -12, -14
	s_add_i32 s13, s13, s73
	s_and_b64 s[60:61], s[60:61], exec
	s_cselect_b32 s15, s1, s21
	s_cselect_b32 s33, s0, s20
	v_lshl_add_u32 v148, s58, 8, v150
	v_mov_b32_e32 v146, s33
	s_waitcnt lgkmcnt(0)
	v_mov_b32_e32 v147, s15
	v_lshl_or_b32 v162, s13, 8, v158
	v_mov_b32_e32 v163, v137
	v_ashrrev_i32_e32 v149, 31, v148
	s_cselect_b32 s13, 9, 11
	v_lshl_add_u64 v[146:147], v[162:163], 1, v[146:147]
	v_lshlrev_b64 v[162:163], s13, v[148:149]
	v_lshl_add_u64 v[166:167], v[162:163], 1, v[146:147]
	v_cvt_pk_bf16_f32 v162, v124, v125
	v_cvt_pk_bf16_f32 v163, v126, v127
	v_cvt_pk_bf16_f32 v164, v120, v121
	v_cvt_pk_bf16_f32 v165, v122, v123
	global_store_dwordx4 v[166:167], v[162:165], off sc0 sc1
	s_nop 1
	v_cvt_pk_bf16_f32 v162, v68, v69
	v_cvt_pk_bf16_f32 v163, v70, v71
	v_cvt_pk_bf16_f32 v164, v64, v65
	v_cvt_pk_bf16_f32 v165, v66, v67
	global_store_dwordx4 v[166:167], v[162:165], off offset:256 sc0 sc1
	s_nop 1
	v_or_b32_e32 v162, 16, v148
	v_ashrrev_i32_e32 v163, 31, v162
	v_lshlrev_b64 v[162:163], s13, v[162:163]
	v_lshl_add_u64 v[166:167], v[162:163], 1, v[146:147]
	v_cvt_pk_bf16_f32 v162, v116, v117
	v_cvt_pk_bf16_f32 v163, v118, v119
	v_cvt_pk_bf16_f32 v164, v112, v113
	v_cvt_pk_bf16_f32 v165, v114, v115
	global_store_dwordx4 v[166:167], v[162:165], off sc0 sc1
	s_nop 1
	v_cvt_pk_bf16_f32 v162, v56, v57
	v_cvt_pk_bf16_f32 v163, v58, v59
	v_cvt_pk_bf16_f32 v164, v48, v49
	v_cvt_pk_bf16_f32 v165, v50, v51
	global_store_dwordx4 v[166:167], v[162:165], off offset:256 sc0 sc1
	s_nop 1
	v_or_b32_e32 v162, 32, v148
	v_ashrrev_i32_e32 v163, 31, v162
	v_lshlrev_b64 v[162:163], s13, v[162:163]
	v_lshl_add_u64 v[166:167], v[162:163], 1, v[146:147]
	v_cvt_pk_bf16_f32 v162, v108, v109
	v_cvt_pk_bf16_f32 v163, v110, v111
	v_cvt_pk_bf16_f32 v164, v104, v105
	v_cvt_pk_bf16_f32 v165, v106, v107
	global_store_dwordx4 v[166:167], v[162:165], off sc0 sc1
	s_nop 1
	v_cvt_pk_bf16_f32 v162, v44, v45
	v_cvt_pk_bf16_f32 v163, v46, v47
	v_cvt_pk_bf16_f32 v164, v40, v41
	v_cvt_pk_bf16_f32 v165, v42, v43
	global_store_dwordx4 v[166:167], v[162:165], off offset:256 sc0 sc1
	s_nop 1
	v_or_b32_e32 v162, 48, v148
	v_ashrrev_i32_e32 v163, 31, v162
	v_lshlrev_b64 v[162:163], s13, v[162:163]
	v_lshl_add_u64 v[166:167], v[162:163], 1, v[146:147]
	v_cvt_pk_bf16_f32 v162, v100, v101
	v_cvt_pk_bf16_f32 v163, v102, v103
	v_cvt_pk_bf16_f32 v164, v96, v97
	v_cvt_pk_bf16_f32 v165, v98, v99
	global_store_dwordx4 v[166:167], v[162:165], off sc0 sc1
	s_nop 1
	v_cvt_pk_bf16_f32 v162, v36, v37
	v_cvt_pk_bf16_f32 v163, v38, v39
	v_cvt_pk_bf16_f32 v164, v32, v33
	v_cvt_pk_bf16_f32 v165, v34, v35
	global_store_dwordx4 v[166:167], v[162:165], off offset:256 sc0 sc1
	s_nop 1
	v_add_u32_e32 v162, 0x80, v148
	v_ashrrev_i32_e32 v163, 31, v162
	v_lshlrev_b64 v[162:163], s13, v[162:163]
	v_lshl_add_u64 v[166:167], v[162:163], 1, v[146:147]
	v_cvt_pk_bf16_f32 v162, v92, v93
	v_cvt_pk_bf16_f32 v163, v94, v95
	v_cvt_pk_bf16_f32 v164, v88, v89
	v_cvt_pk_bf16_f32 v165, v90, v91
	global_store_dwordx4 v[166:167], v[162:165], off sc0 sc1
	s_nop 1
	v_cvt_pk_bf16_f32 v162, v28, v29
	v_cvt_pk_bf16_f32 v163, v30, v31
	v_cvt_pk_bf16_f32 v164, v24, v25
	v_cvt_pk_bf16_f32 v165, v26, v27
	global_store_dwordx4 v[166:167], v[162:165], off offset:256 sc0 sc1
	s_nop 1
	v_add_u32_e32 v162, 0x90, v148
	v_ashrrev_i32_e32 v163, 31, v162
	v_lshlrev_b64 v[162:163], s13, v[162:163]
	v_lshl_add_u64 v[166:167], v[162:163], 1, v[146:147]
	v_cvt_pk_bf16_f32 v162, v84, v85
	v_cvt_pk_bf16_f32 v163, v86, v87
	v_cvt_pk_bf16_f32 v164, v80, v81
	v_cvt_pk_bf16_f32 v165, v82, v83
	global_store_dwordx4 v[166:167], v[162:165], off sc0 sc1
	s_nop 1
	v_cvt_pk_bf16_f32 v162, v20, v21
	v_cvt_pk_bf16_f32 v163, v22, v23
	v_cvt_pk_bf16_f32 v164, v16, v17
	v_cvt_pk_bf16_f32 v165, v18, v19
	global_store_dwordx4 v[166:167], v[162:165], off offset:256 sc0 sc1
	s_nop 1
	v_add_u32_e32 v162, 0xa0, v148
	v_ashrrev_i32_e32 v163, 31, v162
	v_lshlrev_b64 v[162:163], s13, v[162:163]
	v_add_u32_e32 v148, 0xb0, v148
	v_lshl_add_u64 v[166:167], v[162:163], 1, v[146:147]
	v_cvt_pk_bf16_f32 v162, v76, v77
	v_cvt_pk_bf16_f32 v163, v78, v79
	v_ashrrev_i32_e32 v149, 31, v148
	v_cvt_pk_bf16_f32 v164, v72, v73
	v_cvt_pk_bf16_f32 v165, v74, v75
	global_store_dwordx4 v[166:167], v[162:165], off sc0 sc1
	v_lshlrev_b64 v[148:149], s13, v[148:149]
	s_nop 0
	v_cvt_pk_bf16_f32 v162, v12, v13
	v_cvt_pk_bf16_f32 v163, v14, v15
	v_cvt_pk_bf16_f32 v164, v8, v9
	v_cvt_pk_bf16_f32 v165, v10, v11
	global_store_dwordx4 v[166:167], v[162:165], off offset:256 sc0 sc1
	s_nop 1
	v_lshl_add_u64 v[162:163], v[148:149], 1, v[146:147]
	v_cvt_pk_bf16_f32 v146, v60, v61
	v_cvt_pk_bf16_f32 v147, v62, v63
	v_cvt_pk_bf16_f32 v148, v52, v53
	v_cvt_pk_bf16_f32 v149, v54, v55
	global_store_dwordx4 v[162:163], v[146:149], off sc0 sc1
	s_nop 1
	v_cvt_pk_bf16_f32 v146, v4, v5
	v_cvt_pk_bf16_f32 v147, v6, v7
	v_cvt_pk_bf16_f32 v148, v0, v1
	v_cvt_pk_bf16_f32 v149, v2, v3
	global_store_dwordx4 v[162:163], v[146:149], off offset:256 sc0 sc1
	s_cbranch_execnz .LBB0_202

; __device__ __forceinline__ unsigned cvt_pk_bf16(float lo, float hi) { unsigned r; asm volatile("v_cvt_pk_bf16_f32 %0, %1, %2" : "=v"(r) : "v"(lo), "v"(hi)); return r; }
;     __device__ __forceinline__ void operator()(const f32x4 (&acc)[2][2][4][2], const Unit& u, int wr, int wc, int fr, int fq) const {
;     ...
;         if (HEADMAJOR && pn < 12) {
;             bf16_t* base; int ct; float sc = 1.f;
;             if (pn < 4) { base = Q; ct = pn; sc = qscale; } else if (pn < 8) { base = Kb; ct = pn - 4; } else { base = V; ct = pn - 8; }
;             const int b = u.pm >> 3, t0 = (u.pm & 7) * BM + wr * 64 + fr;
; #pragma unroll
;             for (int bj = 0; bj < 2; ++bj) { bf16_t* hb = base + ((size_t)((b * 8 + 2 * ct + bj) * 2048 + t0)) * 128 + wc * 32 + 8 * fq;
; #pragma unroll
;                 for (int ai = 0; ai < 2; ++ai)
; #pragma unroll
;                     for (int m = 0; m < 4; ++m) { const f32x4 v0 = acc[ai][bj][m][0] * sc, v1 = acc[ai][bj][m][1] * sc;
;                         u32x4 w; w.x = cvt_pk_bf16(v0[0], v0[1]); w.y = cvt_pk_bf16(v0[2], v0[3]); w.z = cvt_pk_bf16(v1[0], v1[1]); w.w = cvt_pk_bf16(v1[2], v1[3]);
;                         __builtin_nontemporal_store(w, (u32x4*)(hb + (ai * HALF + m * 16) * 128)); } }
.LBB0_223:
	s_lshl_b32 s13, s58, 8
	s_and_b32 s13, s13, 0x700
	s_add_u32 s66, s66, s22
	s_addc_u32 s67, s67, 0
	s_lshl_b32 s33, s58, 11
	s_lshl_b32 s15, s73, 12
	s_and_b32 s33, s33, 0xffffc000
	s_add_i32 s15, s15, s33
	s_or_b32 s13, s15, s13
	v_add_u32_e32 v148, s13, v150
	v_ashrrev_i32_e32 v149, 31, v148
	s_waitcnt lgkmcnt(0)
	v_lshl_add_u64 v[146:147], s[66:67], 0, v[136:137]
	v_lshlrev_b64 v[162:163], 8, v[148:149]
	v_lshl_add_u64 v[162:163], v[146:147], 0, v[162:163]
	v_pk_mul_f32 v[126:127], v[126:127], s[60:61] op_sel_hi:[1,0]
	v_pk_mul_f32 v[124:125], v[124:125], s[60:61] op_sel_hi:[1,0]
	v_pk_mul_f32 v[164:165], v[122:123], s[60:61] op_sel_hi:[1,0]
	v_pk_mul_f32 v[122:123], v[120:121], s[60:61] op_sel_hi:[1,0]
	v_cvt_pk_bf16_f32 v120, v124, v125
	v_cvt_pk_bf16_f32 v121, v126, v127
	v_pk_mul_f32 v[116:117], v[116:117], s[60:61] op_sel_hi:[1,0]
	v_cvt_pk_bf16_f32 v122, v122, v123
	v_cvt_pk_bf16_f32 v123, v164, v165
	global_store_dwordx4 v[162:163], v[120:123], off sc0 sc1
	v_pk_mul_f32 v[118:119], v[118:119], s[60:61] op_sel_hi:[1,0]
	v_pk_mul_f32 v[110:111], v[110:111], s[60:61] op_sel_hi:[1,0]
	v_pk_mul_f32 v[120:121], v[114:115], s[60:61] op_sel_hi:[1,0]
	v_pk_mul_f32 v[114:115], v[112:113], s[60:61] op_sel_hi:[1,0]
	v_cvt_pk_bf16_f32 v112, v116, v117
	v_add_co_u32_e32 v116, vcc, s89, v162
	v_cvt_pk_bf16_f32 v113, v118, v119
	v_cvt_pk_bf16_f32 v114, v114, v115
	v_cvt_pk_bf16_f32 v115, v120, v121
	v_pk_mul_f32 v[108:109], v[108:109], s[60:61] op_sel_hi:[1,0]
	s_nop 0
	v_addc_co_u32_e32 v117, vcc, 0, v163, vcc
	global_store_dwordx4 v[116:117], v[112:115], off offset:-4096 sc0 sc1
	v_pk_mul_f32 v[100:101], v[100:101], s[60:61] op_sel_hi:[1,0]
	v_pk_mul_f32 v[102:103], v[102:103], s[60:61] op_sel_hi:[1,0]
	v_pk_mul_f32 v[112:113], v[106:107], s[60:61] op_sel_hi:[1,0]
	v_pk_mul_f32 v[106:107], v[104:105], s[60:61] op_sel_hi:[1,0]
	v_cvt_pk_bf16_f32 v104, v108, v109
	v_cvt_pk_bf16_f32 v105, v110, v111
	v_pk_mul_f32 v[92:93], v[92:93], s[60:61] op_sel_hi:[1,0]
	v_cvt_pk_bf16_f32 v106, v106, v107
	v_cvt_pk_bf16_f32 v107, v112, v113
	global_store_dwordx4 v[116:117], v[104:107], off sc0 sc1
	v_pk_mul_f32 v[94:95], v[94:95], s[60:61] op_sel_hi:[1,0]
	v_pk_mul_f32 v[86:87], v[86:87], s[60:61] op_sel_hi:[1,0]
	v_pk_mul_f32 v[104:105], v[98:99], s[60:61] op_sel_hi:[1,0]
	v_pk_mul_f32 v[98:99], v[96:97], s[60:61] op_sel_hi:[1,0]
	v_cvt_pk_bf16_f32 v96, v100, v101
	v_add_co_u32_e32 v100, vcc, s23, v162
	v_cvt_pk_bf16_f32 v97, v102, v103
	v_cvt_pk_bf16_f32 v98, v98, v99
	v_cvt_pk_bf16_f32 v99, v104, v105
	v_pk_mul_f32 v[84:85], v[84:85], s[60:61] op_sel_hi:[1,0]
	s_nop 0
	v_addc_co_u32_e32 v101, vcc, 0, v163, vcc
	global_store_dwordx4 v[100:101], v[96:99], off sc0 sc1
	v_pk_mul_f32 v[76:77], v[76:77], s[60:61] op_sel_hi:[1,0]
	s_mov_b32 s13, 0xb000
	v_pk_mul_f32 v[96:97], v[90:91], s[60:61] op_sel_hi:[1,0]
	v_pk_mul_f32 v[90:91], v[88:89], s[60:61] op_sel_hi:[1,0]
	v_cvt_pk_bf16_f32 v88, v92, v93
	v_add_co_u32_e32 v92, vcc, s72, v162
	v_cvt_pk_bf16_f32 v89, v94, v95
	v_cvt_pk_bf16_f32 v90, v90, v91
	v_cvt_pk_bf16_f32 v91, v96, v97
	v_pk_mul_f32 v[78:79], v[78:79], s[60:61] op_sel_hi:[1,0]
	s_nop 0
	v_addc_co_u32_e32 v93, vcc, 0, v163, vcc
	global_store_dwordx4 v[92:93], v[88:91], off offset:-4096 sc0 sc1
	v_pk_mul_f32 v[60:61], v[60:61], s[60:61] op_sel_hi:[1,0]
	v_pk_mul_f32 v[62:63], v[62:63], s[60:61] op_sel_hi:[1,0]
	v_pk_mul_f32 v[88:89], v[82:83], s[60:61] op_sel_hi:[1,0]
	v_pk_mul_f32 v[82:83], v[80:81], s[60:61] op_sel_hi:[1,0]
	v_cvt_pk_bf16_f32 v80, v84, v85
	v_cvt_pk_bf16_f32 v81, v86, v87
	v_pk_mul_f32 v[64:65], v[64:65], s[60:61] op_sel_hi:[1,0]
	v_cvt_pk_bf16_f32 v82, v82, v83
	v_cvt_pk_bf16_f32 v83, v88, v89
	global_store_dwordx4 v[92:93], v[80:83], off sc0 sc1
	v_pk_mul_f32 v[46:47], v[46:47], s[60:61] op_sel_hi:[1,0]
	v_pk_mul_f32 v[44:45], v[44:45], s[60:61] op_sel_hi:[1,0]
	v_pk_mul_f32 v[80:81], v[74:75], s[60:61] op_sel_hi:[1,0]
	v_pk_mul_f32 v[74:75], v[72:73], s[60:61] op_sel_hi:[1,0]
	v_cvt_pk_bf16_f32 v72, v76, v77
	v_add_co_u32_e32 v76, vcc, s13, v162
	v_cvt_pk_bf16_f32 v73, v78, v79
	v_cvt_pk_bf16_f32 v74, v74, v75
	v_cvt_pk_bf16_f32 v75, v80, v81
	v_pk_mul_f32 v[36:37], v[36:37], s[60:61] op_sel_hi:[1,0]
	s_nop 0
	v_addc_co_u32_e32 v77, vcc, 0, v163, vcc
; __device__ __forceinline__ unsigned cvt_pk_bf16(float lo, float hi) { unsigned r; asm volatile("v_cvt_pk_bf16_f32 %0, %1, %2" : "=v"(r) : "v"(lo), "v"(hi)); return r; }
;     __device__ __forceinline__ void operator()(const f32x4 (&acc)[2][2][4][2], const Unit& u, int wr, int wc, int fr, int fq) const {
;     ...
;             for (int bj = 0; bj < 2; ++bj) { bf16_t* hb = base + ((size_t)((b * 8 + 2 * ct + bj) * 2048 + t0)) * 128 + wc * 32 + 8 * fq;
; #pragma unroll
;                 for (int ai = 0; ai < 2; ++ai)
; #pragma unroll
;                     for (int m = 0; m < 4; ++m) { const f32x4 v0 = acc[ai][bj][m][0] * sc, v1 = acc[ai][bj][m][1] * sc;
;                         u32x4 w; w.x = cvt_pk_bf16(v0[0], v0[1]); w.y = cvt_pk_bf16(v0[2], v0[3]); w.z = cvt_pk_bf16(v1[0], v1[1]); w.w = cvt_pk_bf16(v1[2], v1[3]);
;                         __builtin_nontemporal_store(w, (u32x4*)(hb + (ai * HALF + m * 16) * 128)); } }
	global_store_dwordx4 v[76:77], v[72:75], off offset:-4096 sc0 sc1
	v_pk_mul_f32 v[38:39], v[38:39], s[60:61] op_sel_hi:[1,0]
	v_pk_mul_f32 v[28:29], v[28:29], s[60:61] op_sel_hi:[1,0]
	v_pk_mul_f32 v[72:73], v[54:55], s[60:61] op_sel_hi:[1,0]
	v_pk_mul_f32 v[54:55], v[52:53], s[60:61] op_sel_hi:[1,0]
	v_cvt_pk_bf16_f32 v52, v60, v61
	v_cvt_pk_bf16_f32 v53, v62, v63
	v_pk_mul_f32 v[62:63], v[66:67], s[60:61] op_sel_hi:[1,0]
	v_cvt_pk_bf16_f32 v54, v54, v55
	v_cvt_pk_bf16_f32 v55, v72, v73
	global_store_dwordx4 v[76:77], v[52:55], off sc0 sc1
	v_pk_mul_f32 v[30:31], v[30:31], s[60:61] op_sel_hi:[1,0]
	v_pk_mul_f32 v[22:23], v[22:23], s[60:61] op_sel_hi:[1,0]
	v_add_u32_e32 v52, 0x800, v148
	v_ashrrev_i32_e32 v53, 31, v52
	v_lshlrev_b64 v[52:53], 8, v[52:53]
	v_lshl_add_u64 v[60:61], v[146:147], 0, v[52:53]
	v_pk_mul_f32 v[52:53], v[68:69], s[60:61] op_sel_hi:[1,0]
	v_pk_mul_f32 v[54:55], v[70:71], s[60:61] op_sel_hi:[1,0]
	v_cvt_pk_bf16_f32 v52, v52, v53
	v_pk_mul_f32 v[20:21], v[20:21], s[60:61] op_sel_hi:[1,0]
	v_cvt_pk_bf16_f32 v53, v54, v55
	v_cvt_pk_bf16_f32 v54, v64, v65
	v_cvt_pk_bf16_f32 v55, v62, v63
	global_store_dwordx4 v[60:61], v[52:55], off sc0 sc1
	v_pk_mul_f32 v[12:13], v[12:13], s[60:61] op_sel_hi:[1,0]
	s_mov_b32 s13, 0xa000
	v_pk_mul_f32 v[52:53], v[58:59], s[60:61] op_sel_hi:[1,0]
	v_pk_mul_f32 v[54:55], v[56:57], s[60:61] op_sel_hi:[1,0]
	v_pk_mul_f32 v[56:57], v[50:51], s[60:61] op_sel_hi:[1,0]
	v_pk_mul_f32 v[50:51], v[48:49], s[60:61] op_sel_hi:[1,0]
	v_cvt_pk_bf16_f32 v48, v54, v55
	v_cvt_pk_bf16_f32 v49, v52, v53
	v_add_co_u32_e32 v52, vcc, s89, v60
	v_cvt_pk_bf16_f32 v50, v50, v51
	v_cvt_pk_bf16_f32 v51, v56, v57
	v_pk_mul_f32 v[14:15], v[14:15], s[60:61] op_sel_hi:[1,0]
	s_nop 0
	v_addc_co_u32_e32 v53, vcc, 0, v61, vcc
	global_store_dwordx4 v[52:53], v[48:51], off offset:-4096 sc0 sc1
	v_pk_mul_f32 v[4:5], v[4:5], s[60:61] op_sel_hi:[1,0]
	v_pk_mul_f32 v[6:7], v[6:7], s[60:61] op_sel_hi:[1,0]
	v_pk_mul_f32 v[48:49], v[42:43], s[60:61] op_sel_hi:[1,0]
	v_pk_mul_f32 v[42:43], v[40:41], s[60:61] op_sel_hi:[1,0]
	v_cvt_pk_bf16_f32 v40, v44, v45
	v_cvt_pk_bf16_f32 v41, v46, v47
	s_nop 0
	v_cvt_pk_bf16_f32 v42, v42, v43
	v_cvt_pk_bf16_f32 v43, v48, v49
	global_store_dwordx4 v[52:53], v[40:43], off sc0 sc1
	s_nop 1
	v_pk_mul_f32 v[40:41], v[34:35], s[60:61] op_sel_hi:[1,0]
	v_pk_mul_f32 v[34:35], v[32:33], s[60:61] op_sel_hi:[1,0]
	v_cvt_pk_bf16_f32 v32, v36, v37
	v_add_co_u32_e32 v36, vcc, s23, v60
	v_cvt_pk_bf16_f32 v33, v38, v39
	v_cvt_pk_bf16_f32 v34, v34, v35
	v_cvt_pk_bf16_f32 v35, v40, v41
	s_nop 1
	v_addc_co_u32_e32 v37, vcc, 0, v61, vcc
	global_store_dwordx4 v[36:37], v[32:35], off sc0 sc1
	s_nop 1
	v_pk_mul_f32 v[32:33], v[26:27], s[60:61] op_sel_hi:[1,0]
	v_pk_mul_f32 v[26:27], v[24:25], s[60:61] op_sel_hi:[1,0]
	v_cvt_pk_bf16_f32 v24, v28, v29
	v_add_co_u32_e32 v28, vcc, s72, v60
	v_cvt_pk_bf16_f32 v25, v30, v31
	v_cvt_pk_bf16_f32 v26, v26, v27
	v_cvt_pk_bf16_f32 v27, v32, v33
	s_nop 1
	v_addc_co_u32_e32 v29, vcc, 0, v61, vcc
	global_store_dwordx4 v[28:29], v[24:27], off offset:-4096 sc0 sc1
	s_nop 1
	v_pk_mul_f32 v[24:25], v[18:19], s[60:61] op_sel_hi:[1,0]
	v_pk_mul_f32 v[18:19], v[16:17], s[60:61] op_sel_hi:[1,0]
	v_cvt_pk_bf16_f32 v16, v20, v21
	v_cvt_pk_bf16_f32 v17, v22, v23
	s_nop 0
	v_cvt_pk_bf16_f32 v18, v18, v19
	v_cvt_pk_bf16_f32 v19, v24, v25
	global_store_dwordx4 v[28:29], v[16:19], off sc0 sc1
	s_nop 1
	v_pk_mul_f32 v[16:17], v[10:11], s[60:61] op_sel_hi:[1,0]
	v_pk_mul_f32 v[10:11], v[8:9], s[60:61] op_sel_hi:[1,0]
	v_cvt_pk_bf16_f32 v8, v12, v13
	v_add_co_u32_e32 v12, vcc, s13, v60
	v_cvt_pk_bf16_f32 v9, v14, v15
	v_cvt_pk_bf16_f32 v10, v10, v11
	v_cvt_pk_bf16_f32 v11, v16, v17
	s_nop 1
	v_addc_co_u32_e32 v13, vcc, 0, v61, vcc
	global_store_dwordx4 v[12:13], v[8:11], off sc0 sc1
	s_nop 1
	v_pk_mul_f32 v[8:9], v[2:3], s[60:61] op_sel_hi:[1,0]
	v_pk_mul_f32 v[2:3], v[0:1], s[60:61] op_sel_hi:[1,0]
	v_cvt_pk_bf16_f32 v0, v4, v5
	v_add_co_u32_e32 v4, vcc, 0xb000, v60
	v_cvt_pk_bf16_f32 v1, v6, v7
	v_cvt_pk_bf16_f32 v2, v2, v3
	v_cvt_pk_bf16_f32 v3, v8, v9
	s_nop 1
	v_addc_co_u32_e32 v5, vcc, 0, v61, vcc
	global_store_dwordx4 v[4:5], v[0:3], off sc0 sc1
	s_andn2_b64 vcc, exec, s[4:5]
	s_mov_b64 s[4:5], -1
	s_cbranch_vccnz .LBB0_193
